# NSA selected-branch head: per-lane selection mask words cached in registers, reloaded every 32 blocks
# speedup vs baseline: 1.0045x; 1.0045x over previous
; __device__ __forceinline__ void nsa_wg_task(bf16_t* zb, const bf16_t* kcb, const bf16_t* vctb, const bf16_t* vst, const bf16_t* vwt, int g, int T0, float* accb, LAS unsigned char* lds, int wave, int lane, int tid) {
;     ...
;             const int s = i - 2 * nc, kb0 = s * 64;
;             bool any[2], mine[2], all4[2];
;             const unsigned mwd0 = wM[ti * 4 + (s >> 5)], mwd1 = wM[(4 + ti) * 4 + (s >> 5)];
;             nsa_loadk(kbuf, offk0, offk1, ka, kb);
; #pragma unroll
;             for (int r = 0; r < 2; ++r) { const unsigned mwd = r == 0 ? mwd0 : mwd1; mine[r] = ((mwd >> (s & 31)) & 1u) != 0u; const unsigned long long bal = __ballot(mine[r]); any[r] = bal != 0ull && kb0 <= tmax[r]; all4[r] = bal == ~0ull; }
.LBB0_209:
	s_add_i32 s44, s34, s75
	s_cmp_gt_i32 s44, s38
	s_mov_b64 s[20:21], -1
	s_cbranch_scc1 .LBB0_208
	s_add_i32 s2, s34, s1
	s_lshl_b32 s2, s2, 14
	s_add_i32 s45, s2, 0
	s_cmp_ge_i32 s44, s70
	s_cbranch_scc0 .LBB0_334
	s_cmp_ge_i32 s44, s71
	s_cbranch_scc0 .LBB0_260
	s_cmp_gt_i32 s44, s84
	s_cbranch_scc1 .LBB0_240
	s_sub_i32 s2, s44, s71
	s_ashr_i32 s20, s2, 5
	s_waitcnt lgkmcnt(0)
	s_and_b32 s21, s2, 31
	s_cmp_lg_u32 s21, 0
	s_cbranch_scc1 .Lsel_mask_cached
	v_lshl_add_u32 v16, s20, 2, v207
	ds_read2_b32 v[242:243], v16 offset1:16
	s_waitcnt lgkmcnt(0)
.Lsel_mask_cached:
	s_lshl_b32 s21, 1, s2
	s_lshl_b32 s20, s2, 6
	v_mov_b64_e32 v[32:33], v[84:85]
	v_mov_b64_e32 v[36:37], v[88:89]
	v_and_b32_e32 v16, s21, v242
	v_cmp_ne_u32_e64 s[24:25], 0, v16
	s_cmp_lg_u64 s[24:25], 0
	s_cselect_b64 s[22:23], -1, 0
	s_cmp_le_i32 s20, s85
	v_and_b32_e32 v17, s21, v243
	s_cselect_b64 s[28:29], -1, 0
	s_and_b64 s[56:57], s[22:23], s[28:29]
	v_cmp_ne_u32_e64 s[22:23], 0, v17
	s_cmp_lg_u64 s[22:23], 0
	s_cselect_b64 s[28:29], -1, 0
	s_cmp_le_i32 s20, s81
	s_cselect_b64 s[94:95], -1, 0
	s_and_b64 s[28:29], s[28:29], s[94:95]
	s_or_b64 s[94:95], s[56:57], s[28:29]
	s_cmp_eq_u32 s2, s61
	s_cbranch_scc1 .Lnsa_sel_noskip
	s_andn2_b64 vcc, exec, s[94:95]
	s_cbranch_vccnz .LBB0_345
	s_mov_b64 s[98:99], s[24:25]
	s_mov_b64 s[100:101], s[22:23]
	s_branch .Lsel_fast
